# scan staging waves: set A loaded straight into its home registers (copy + vmcnt(0) removed), flush no longer drains loads, convert steps wait vmcnt(12) so the other set's prefetch stays in flight
# baseline (speedup 1.0000x reference)
.LBB0_1098:
	s_and_b64 vcc, exec, s[92:93]
	s_cbranch_vccz .LBB0_1090
	s_cmp_eq_u32 s9, 63
	s_cbranch_scc1 .LBB0_1112
	s_bitcmp1_b32 s9, 0
	s_cselect_b64 s[6:7], -1, 0
	s_mov_b64 s[92:93], -1
	s_and_b64 vcc, exec, s[6:7]
	s_cbranch_vccz .LBB0_1106
	s_waitcnt vmcnt(12)
	v_lshlrev_b32_e32 v24, 16, v0
	s_nop 0
	v_lshlrev_b32_e32 v28, 16, v12
	v_mul_f32_e32 v24, 0xbfb8aa3b, v24
	v_and_b32_e32 v25, 0xffff0000, v0
	v_exp_f32_e32 v78, v24
	v_mul_f32_e32 v24, 0xbfb8aa3b, v28
	v_and_b32_e32 v29, 0xffff0000, v12
	v_exp_f32_e32 v80, v24
	v_mul_f32_e32 v24, 0xbfb8aa3b, v25
	v_lshlrev_b32_e32 v26, 16, v1
	v_exp_f32_e32 v79, v24
	v_mul_f32_e32 v24, 0xbfb8aa3b, v29
	v_lshlrev_b32_e32 v30, 16, v13
	v_exp_f32_e32 v81, v24
	v_mul_f32_e32 v24, 0xbfb8aa3b, v26
	v_and_b32_e32 v27, 0xffff0000, v1
	v_exp_f32_e32 v82, v24
	v_mul_f32_e32 v24, 0xbfb8aa3b, v30
	v_lshlrev_b32_e32 v62, 16, v2
	v_and_b32_e32 v63, 0xffff0000, v2
	v_lshlrev_b32_e32 v66, 16, v6
	v_and_b32_e32 v67, 0xffff0000, v6
	v_and_b32_e32 v31, 0xffff0000, v13
	v_lshlrev_b32_e32 v74, 16, v16
	v_and_b32_e32 v75, 0xffff0000, v16
	v_exp_f32_e32 v84, v24
	v_mul_f32_e32 v24, 0xbfb8aa3b, v27
	v_lshlrev_b32_e32 v64, 16, v3
	v_and_b32_e32 v65, 0xffff0000, v3
	v_lshlrev_b32_e32 v68, 16, v7
	v_and_b32_e32 v69, 0xffff0000, v7
	v_lshlrev_b32_e32 v76, 16, v17
	v_and_b32_e32 v77, 0xffff0000, v17
	v_exp_f32_e32 v83, v24
	v_mul_f32_e32 v24, 0xbfb8aa3b, v31
	v_pk_mul_f32 v[26:27], v[66:67], v[74:75]
	v_pk_mul_f32 v[30:31], v[62:63], v[74:75]
	v_exp_f32_e32 v85, v24
	v_pk_mul_f32 v[24:25], v[68:69], v[76:77]
	v_pk_mul_f32 v[28:29], v[64:65], v[76:77]
	v_mov_b32_e32 v94, v26
	v_mov_b32_e32 v95, v30
	v_mov_b32_e32 v30, v27
	v_pk_add_f32 v[26:27], v[94:95], v[30:31]
	v_mov_b32_e32 v30, v24
	v_mov_b32_e32 v31, v28
	v_mov_b32_e32 v28, v25
	v_pk_add_f32 v[24:25], v[30:31], v[28:29]
	v_lshlrev_b32_e32 v70, 16, v8
	v_pk_add_f32 v[24:25], v[26:27], v[24:25]
	v_and_b32_e32 v71, 0xffff0000, v8
	v_lshlrev_b32_e32 v72, 16, v9
	v_mov_b32_dpp v26, v24 row_mirror row_mask:0xf bank_mask:0xf bound_ctrl:1
	v_mov_b32_dpp v27, v25 row_mirror row_mask:0xf bank_mask:0xf bound_ctrl:1
	v_pk_add_f32 v[24:25], v[24:25], v[26:27]
	v_and_b32_e32 v73, 0xffff0000, v9
	v_pk_mul_f32 v[86:87], v[68:69], v[72:73]
	v_mov_b32_dpp v26, v24 row_half_mirror row_mask:0xf bank_mask:0xf bound_ctrl:1
	v_mov_b32_dpp v27, v25 row_half_mirror row_mask:0xf bank_mask:0xf bound_ctrl:1
	v_pk_add_f32 v[24:25], v[24:25], v[26:27]
	v_pk_mul_f32 v[88:89], v[66:67], v[70:71]
	v_pk_mul_f32 v[90:91], v[64:65], v[72:73]
	v_pk_mul_f32 v[92:93], v[62:63], v[70:71]
	v_mov_b32_dpp v26, v24 quad_perm:[1,0,3,2] row_mask:0xf bank_mask:0xf bound_ctrl:1
	v_mov_b32_dpp v27, v25 quad_perm:[1,0,3,2] row_mask:0xf bank_mask:0xf bound_ctrl:1
	v_pk_add_f32 v[24:25], v[24:25], v[26:27]
	v_mov_b32_e32 v26, v88
	v_mov_b32_e32 v27, v92
	v_mov_b32_e32 v92, v89
	v_mov_b32_e32 v28, v86
	v_mov_b32_e32 v29, v90
	v_mov_b32_e32 v90, v87
	v_pk_add_f32 v[26:27], v[26:27], v[92:93]
	v_pk_add_f32 v[28:29], v[28:29], v[90:91]
	v_lshlrev_b32_e32 v32, 16, v4
	v_pk_add_f32 v[26:27], v[26:27], v[28:29]
	v_and_b32_e32 v33, 0xffff0000, v4
	v_lshlrev_b32_e32 v34, 16, v5
	v_mov_b32_dpp v28, v26 row_mirror row_mask:0xf bank_mask:0xf bound_ctrl:1
	v_mov_b32_dpp v29, v27 row_mirror row_mask:0xf bank_mask:0xf bound_ctrl:1
	v_and_b32_e32 v35, 0xffff0000, v5
	v_pk_add_f32 v[26:27], v[26:27], v[28:29]
	ds_write_b128 v152, v[32:35]
	v_pk_mul_f32 v[34:35], v[82:83], v[76:77]
	v_mov_b32_dpp v28, v26 row_half_mirror row_mask:0xf bank_mask:0xf bound_ctrl:1
	v_mov_b32_dpp v29, v27 row_half_mirror row_mask:0xf bank_mask:0xf bound_ctrl:1
	v_pk_mul_f32 v[32:33], v[78:79], v[74:75]
	v_pk_add_f32 v[26:27], v[26:27], v[28:29]
	ds_write_b128 v152, v[32:35] offset:256
	v_pk_mul_f32 v[34:35], v[82:83], v[72:73]
	v_pk_mul_f32 v[32:33], v[78:79], v[70:71]
	v_lshlrev_b32_e32 v54, 16, v20
	v_and_b32_e32 v55, 0xffff0000, v20
	v_lshlrev_b32_e32 v56, 16, v21
	v_and_b32_e32 v57, 0xffff0000, v21
	v_mov_b32_dpp v28, v26 quad_perm:[1,0,3,2] row_mask:0xf bank_mask:0xf bound_ctrl:1
	v_mov_b32_dpp v29, v27 quad_perm:[1,0,3,2] row_mask:0xf bank_mask:0xf bound_ctrl:1
	ds_write_b128 v152, v[32:35] offset:512
	ds_write_b128 v152, v[54:57] offset:768
	v_pk_mul_f32 v[34:35], v[82:83], v[84:85]
	v_pk_mul_f32 v[32:33], v[78:79], v[80:81]
	v_pk_add_f32 v[28:29], v[26:27], v[28:29]
	ds_write_b128 v152, v[32:35] offset:1024
	v_pk_mul_f32 v[34:35], v[84:85], v[68:69]
	v_pk_mul_f32 v[32:33], v[80:81], v[66:67]
	v_mov_b32_dpp v26, v24 quad_perm:[2,3,0,1] row_mask:0xf bank_mask:0xf bound_ctrl:1
	v_mov_b32_dpp v27, v25 quad_perm:[2,3,0,1] row_mask:0xf bank_mask:0xf bound_ctrl:1
	v_mov_b32_dpp v30, v28 quad_perm:[2,3,0,1] row_mask:0xf bank_mask:0xf bound_ctrl:1
	v_mov_b32_dpp v31, v29 quad_perm:[2,3,0,1] row_mask:0xf bank_mask:0xf bound_ctrl:1
	ds_write_b128 v152, v[32:35] offset:1280
	v_pk_mul_f32 v[34:35], v[84:85], v[64:65]
	v_pk_mul_f32 v[32:33], v[80:81], v[62:63]
	v_lshlrev_b32_e32 v36, 16, v10
	v_and_b32_e32 v37, 0xffff0000, v10
	v_lshlrev_b32_e32 v38, 16, v11
	v_and_b32_e32 v39, 0xffff0000, v11
	v_lshlrev_b32_e32 v40, 16, v14
	v_and_b32_e32 v41, 0xffff0000, v14
	v_lshlrev_b32_e32 v42, 16, v15
	v_and_b32_e32 v43, 0xffff0000, v15
	v_lshlrev_b32_e32 v44, 16, v18
	v_and_b32_e32 v45, 0xffff0000, v18
	v_lshlrev_b32_e32 v46, 16, v19
	v_and_b32_e32 v47, 0xffff0000, v19
	v_lshlrev_b32_e32 v58, 16, v22
	v_and_b32_e32 v59, 0xffff0000, v22
	v_lshlrev_b32_e32 v60, 16, v23
	v_and_b32_e32 v61, 0xffff0000, v23
	ds_write_b128 v152, v[32:35] offset:1536
	ds_write_b128 v152, v[44:47] offset:1792
	ds_write_b128 v152, v[40:43] offset:2048
	ds_write_b128 v152, v[36:39] offset:2304
	ds_write_b128 v152, v[58:61] offset:2560
	s_and_saveexec_b64 s[92:93], s[38:39]
	v_pk_add_f32 v[28:29], v[28:29], v[30:31]
	v_pk_add_f32 v[26:27], v[24:25], v[26:27]
	ds_write_b128 v103, v[26:29] offset:2816
	s_or_b64 exec, exec, s[92:93]
	v_mov_b64_e32 v[34:35], v[10:11]
	v_mov_b64_e32 v[46:47], v[22:23]
	s_cmp_gt_u32 s9, 60
	v_mov_b64_e32 v[32:33], v[8:9]
	v_mov_b64_e32 v[30:31], v[6:7]
	v_mov_b64_e32 v[28:29], v[4:5]
	v_mov_b64_e32 v[26:27], v[2:3]
	v_mov_b64_e32 v[24:25], v[0:1]
	v_mov_b64_e32 v[44:45], v[20:21]
	v_mov_b64_e32 v[42:43], v[18:19]
	v_mov_b64_e32 v[40:41], v[16:17]
	v_mov_b64_e32 v[38:39], v[14:15]
	v_mov_b64_e32 v[36:37], v[12:13]
	s_cbranch_scc1 .LBB0_1105
	s_lshl_b32 s6, s9, 5
	s_add_i32 s24, s6, 0x60
	v_lshl_add_u64 v[24:25], v[104:105], 0, s[24:25]
	v_mad_u64_u32 v[46:47], s[6:7], v24, s95, v[138:139]
	v_mad_i32_i24 v47, v25, s95, v47
	global_load_dwordx2 v[0:1], v[46:47], off
	global_load_dwordx2 v[2:3], v[46:47], off offset:128
	global_load_dwordx2 v[4:5], v[46:47], off offset:256
	global_load_dwordx2 v[6:7], v[46:47], off offset:384
	global_load_dwordx2 v[12:13], v[46:47], off offset:768
	global_load_dwordx2 v[14:15], v[46:47], off offset:896
	global_load_dwordx2 v[8:9], v[46:47], off offset:512
	global_load_dwordx2 v[10:11], v[46:47], off offset:640
	global_load_dwordx2 v[16:17], v[46:47], off offset:1024
	global_load_dwordx2 v[18:19], v[46:47], off offset:1152
	global_load_dwordx2 v[20:21], v[46:47], off offset:1280
	s_nop 0
	global_load_dwordx2 v[22:23], v[46:47], off offset:1408

.LBB0_1106:
	s_and_b64 vcc, exec, s[92:93]
	s_cbranch_vccz .LBB0_1111
	s_waitcnt vmcnt(12)
	s_cmp_lt_u32 s9, 62
	s_cbranch_scc1 .Lstg_ok
	s_waitcnt vmcnt(0)
.Lstg_ok:
	v_lshlrev_b32_e32 v24, 16, v122
	s_nop 0
	v_lshlrev_b32_e32 v28, 16, v116
	v_mul_f32_e32 v24, 0xbfb8aa3b, v24
	v_and_b32_e32 v25, 0xffff0000, v122
	v_exp_f32_e32 v78, v24
	v_mul_f32_e32 v24, 0xbfb8aa3b, v28
	v_and_b32_e32 v29, 0xffff0000, v116
	v_exp_f32_e32 v80, v24
	v_mul_f32_e32 v24, 0xbfb8aa3b, v25
	v_lshlrev_b32_e32 v26, 16, v123
	v_exp_f32_e32 v79, v24
	v_mul_f32_e32 v24, 0xbfb8aa3b, v29
	v_lshlrev_b32_e32 v30, 16, v117
	v_exp_f32_e32 v81, v24
	v_mul_f32_e32 v24, 0xbfb8aa3b, v26
	v_and_b32_e32 v27, 0xffff0000, v123
	v_exp_f32_e32 v82, v24
	v_mul_f32_e32 v24, 0xbfb8aa3b, v30
	v_lshlrev_b32_e32 v62, 16, v112
	v_and_b32_e32 v63, 0xffff0000, v112
	v_lshlrev_b32_e32 v66, 16, v120
	v_and_b32_e32 v67, 0xffff0000, v120
	v_and_b32_e32 v31, 0xffff0000, v117
	v_lshlrev_b32_e32 v74, 16, v124
	v_and_b32_e32 v75, 0xffff0000, v124
	v_exp_f32_e32 v84, v24
	v_mul_f32_e32 v24, 0xbfb8aa3b, v27
	v_lshlrev_b32_e32 v64, 16, v113
	v_and_b32_e32 v65, 0xffff0000, v113
	v_lshlrev_b32_e32 v68, 16, v121
	v_and_b32_e32 v69, 0xffff0000, v121
	v_lshlrev_b32_e32 v76, 16, v125
	v_and_b32_e32 v77, 0xffff0000, v125
	v_exp_f32_e32 v83, v24
	v_mul_f32_e32 v24, 0xbfb8aa3b, v31
	v_pk_mul_f32 v[26:27], v[66:67], v[74:75]
	v_pk_mul_f32 v[30:31], v[62:63], v[74:75]
	v_exp_f32_e32 v85, v24
	v_pk_mul_f32 v[24:25], v[68:69], v[76:77]
	v_pk_mul_f32 v[28:29], v[64:65], v[76:77]
	v_mov_b32_e32 v94, v26
	v_mov_b32_e32 v95, v30
	v_mov_b32_e32 v30, v27
	v_pk_add_f32 v[26:27], v[94:95], v[30:31]
	v_mov_b32_e32 v30, v24
	v_mov_b32_e32 v31, v28
	v_mov_b32_e32 v28, v25
	v_pk_add_f32 v[24:25], v[30:31], v[28:29]
	v_lshlrev_b32_e32 v70, 16, v126
	v_pk_add_f32 v[24:25], v[26:27], v[24:25]
	v_and_b32_e32 v71, 0xffff0000, v126
	v_lshlrev_b32_e32 v72, 16, v127
	v_mov_b32_dpp v26, v24 row_mirror row_mask:0xf bank_mask:0xf bound_ctrl:1
	v_mov_b32_dpp v27, v25 row_mirror row_mask:0xf bank_mask:0xf bound_ctrl:1
	v_pk_add_f32 v[24:25], v[24:25], v[26:27]
	v_and_b32_e32 v73, 0xffff0000, v127
	v_pk_mul_f32 v[86:87], v[72:73], v[68:69]
	v_mov_b32_dpp v26, v24 row_half_mirror row_mask:0xf bank_mask:0xf bound_ctrl:1
	v_mov_b32_dpp v27, v25 row_half_mirror row_mask:0xf bank_mask:0xf bound_ctrl:1
	v_pk_add_f32 v[24:25], v[24:25], v[26:27]
	v_pk_mul_f32 v[88:89], v[70:71], v[66:67]
	v_pk_mul_f32 v[90:91], v[72:73], v[64:65]
	v_pk_mul_f32 v[92:93], v[70:71], v[62:63]
	v_mov_b32_dpp v26, v24 quad_perm:[1,0,3,2] row_mask:0xf bank_mask:0xf bound_ctrl:1
	v_mov_b32_dpp v27, v25 quad_perm:[1,0,3,2] row_mask:0xf bank_mask:0xf bound_ctrl:1
	v_pk_add_f32 v[24:25], v[24:25], v[26:27]
	v_mov_b32_e32 v26, v88
	v_mov_b32_e32 v27, v92
	v_mov_b32_e32 v92, v89
	v_mov_b32_e32 v28, v86
	v_mov_b32_e32 v29, v90
	v_mov_b32_e32 v90, v87
	v_pk_add_f32 v[26:27], v[26:27], v[92:93]
	v_pk_add_f32 v[28:29], v[28:29], v[90:91]
	v_lshlrev_b32_e32 v32, 16, v114
	v_pk_add_f32 v[26:27], v[26:27], v[28:29]
	v_and_b32_e32 v33, 0xffff0000, v114
	v_lshlrev_b32_e32 v34, 16, v115
	v_mov_b32_dpp v28, v26 row_mirror row_mask:0xf bank_mask:0xf bound_ctrl:1
	v_mov_b32_dpp v29, v27 row_mirror row_mask:0xf bank_mask:0xf bound_ctrl:1
	v_and_b32_e32 v35, 0xffff0000, v115
	v_pk_add_f32 v[26:27], v[26:27], v[28:29]
	ds_write_b128 v152, v[32:35] offset:45568
	v_pk_mul_f32 v[34:35], v[82:83], v[76:77]
	v_mov_b32_dpp v28, v26 row_half_mirror row_mask:0xf bank_mask:0xf bound_ctrl:1
	v_mov_b32_dpp v29, v27 row_half_mirror row_mask:0xf bank_mask:0xf bound_ctrl:1
	v_pk_mul_f32 v[32:33], v[78:79], v[74:75]
	v_pk_add_f32 v[26:27], v[26:27], v[28:29]
	ds_write_b128 v152, v[32:35] offset:45824
	v_pk_mul_f32 v[34:35], v[82:83], v[72:73]
	v_pk_mul_f32 v[32:33], v[78:79], v[70:71]
	v_lshlrev_b32_e32 v54, 16, v130
	v_and_b32_e32 v55, 0xffff0000, v130
	v_lshlrev_b32_e32 v56, 16, v131
	v_and_b32_e32 v57, 0xffff0000, v131
	v_mov_b32_dpp v28, v26 quad_perm:[1,0,3,2] row_mask:0xf bank_mask:0xf bound_ctrl:1
	v_mov_b32_dpp v29, v27 quad_perm:[1,0,3,2] row_mask:0xf bank_mask:0xf bound_ctrl:1
	ds_write_b128 v152, v[32:35] offset:46080
	ds_write_b128 v152, v[54:57] offset:46336
	v_pk_mul_f32 v[34:35], v[82:83], v[84:85]
	v_pk_mul_f32 v[32:33], v[78:79], v[80:81]
	v_pk_add_f32 v[28:29], v[26:27], v[28:29]
	ds_write_b128 v152, v[32:35] offset:46592
	v_pk_mul_f32 v[34:35], v[84:85], v[68:69]
	v_pk_mul_f32 v[32:33], v[80:81], v[66:67]
	v_mov_b32_dpp v26, v24 quad_perm:[2,3,0,1] row_mask:0xf bank_mask:0xf bound_ctrl:1
	v_mov_b32_dpp v27, v25 quad_perm:[2,3,0,1] row_mask:0xf bank_mask:0xf bound_ctrl:1
	v_mov_b32_dpp v30, v28 quad_perm:[2,3,0,1] row_mask:0xf bank_mask:0xf bound_ctrl:1
	v_mov_b32_dpp v31, v29 quad_perm:[2,3,0,1] row_mask:0xf bank_mask:0xf bound_ctrl:1
	ds_write_b128 v152, v[32:35] offset:46848
	v_pk_mul_f32 v[34:35], v[84:85], v[64:65]
	v_pk_mul_f32 v[32:33], v[80:81], v[62:63]
	v_lshlrev_b32_e32 v36, 16, v132
	v_and_b32_e32 v37, 0xffff0000, v132
	v_lshlrev_b32_e32 v38, 16, v133
	v_and_b32_e32 v39, 0xffff0000, v133
	v_lshlrev_b32_e32 v40, 16, v118
	v_and_b32_e32 v41, 0xffff0000, v118
	v_lshlrev_b32_e32 v42, 16, v119
	v_and_b32_e32 v43, 0xffff0000, v119
	v_lshlrev_b32_e32 v44, 16, v128
	v_and_b32_e32 v45, 0xffff0000, v128
	v_lshlrev_b32_e32 v46, 16, v129
	v_and_b32_e32 v47, 0xffff0000, v129
	v_lshlrev_b32_e32 v58, 16, v134
	v_and_b32_e32 v59, 0xffff0000, v134
	v_lshlrev_b32_e32 v60, 16, v135
	v_and_b32_e32 v61, 0xffff0000, v135
	ds_write_b128 v152, v[32:35] offset:47104
	ds_write_b128 v152, v[44:47] offset:47360
	ds_write_b128 v152, v[40:43] offset:47616
	ds_write_b128 v152, v[36:39] offset:47872
	ds_write_b128 v152, v[58:61] offset:48128
	s_and_saveexec_b64 s[92:93], s[38:39]
	v_pk_add_f32 v[28:29], v[28:29], v[30:31]
	v_pk_add_f32 v[26:27], v[24:25], v[26:27]
	ds_write_b128 v103, v[26:29] offset:48384
	s_or_b64 exec, exec, s[92:93]
	s_cmp_gt_u32 s9, 60
	s_cbranch_scc1 .LBB0_1112
	s_lshl_b32 s6, s9, 5
	s_add_i32 s24, s6, 0x60
	v_lshl_add_u64 v[24:25], v[104:105], 0, s[24:25]
	v_mad_u64_u32 v[26:27], s[6:7], v24, s95, v[138:139]
	v_mad_i32_i24 v27, v25, s95, v27
	global_load_dwordx2 v[122:123], v[26:27], off
	global_load_dwordx2 v[112:113], v[26:27], off offset:128
	global_load_dwordx2 v[114:115], v[26:27], off offset:256
	global_load_dwordx2 v[120:121], v[26:27], off offset:384
	global_load_dwordx2 v[116:117], v[26:27], off offset:768
	global_load_dwordx2 v[118:119], v[26:27], off offset:896
	global_load_dwordx2 v[126:127], v[26:27], off offset:512
	global_load_dwordx2 v[132:133], v[26:27], off offset:640
	global_load_dwordx2 v[124:125], v[26:27], off offset:1024
	global_load_dwordx2 v[128:129], v[26:27], off offset:1152
	global_load_dwordx2 v[130:131], v[26:27], off offset:1280
	global_load_dwordx2 v[134:135], v[26:27], off offset:1408
	s_branch .LBB0_1112
.LBB0_1111:
.LBB0_1112:
	s_cmp_gt_u32 s9, 1
	s_cselect_b64 s[6:7], -1, 0
	s_and_b64 s[6:7], s[6:7], s[40:41]
	s_and_saveexec_b64 s[92:93], s[6:7]
	s_cbranch_execz .LBB0_1114
	s_add_i32 s24, s9, -2
	s_lshl_b32 s6, s24, 11
	s_and_b32 s6, s6, 0x1800
	v_add_u32_e32 v24, s6, v157
	s_lshl_b64 s[6:7], s[24:25], 16
	ds_read_b128 v[24:27], v24
	v_lshl_add_u64 v[28:29], v[136:137], 0, s[6:7]
	s_waitcnt lgkmcnt(0)
	global_store_dwordx4 v[28:29], v[24:27], off
	s_nop 1
